# N0 wave reductions (H-row sum of squares and bias GEMVs) via DPP + permlane swaps instead of ds_bpermute round trips
# baseline (speedup 1.0000x reference)
.LBB0_173:
	s_cmpk_lt_i32 s11, 0x2000
	s_cselect_b64 s[28:29], -1, 0
	s_and_b64 s[30:31], s[28:29], exec
	s_cselect_b32 s31, s0, s35
	s_cselect_b32 s30, s1, s34
	v_lshl_add_u64 v[36:37], s[30:31], 0, v[22:23]
	global_load_dwordx4 v[12:15], v[36:37], off nt
	global_load_dwordx4 v[8:11], v[36:37], off offset:1024 nt
	global_load_dwordx4 v[4:7], v[36:37], off offset:2048 nt
	global_load_dwordx4 v[0:3], v[36:37], off offset:3072 nt
	s_waitcnt vmcnt(3)
	v_mul_f32_e32 v35, v13, v13
	v_mul_f32_e32 v36, v15, v15
	s_waitcnt vmcnt(2)
	v_mul_f32_e32 v37, v9, v9
	v_mul_f32_e32 v38, v11, v11
	s_waitcnt vmcnt(1)
	v_mul_f32_e32 v39, v5, v5
	v_mul_f32_e32 v40, v7, v7
	v_fmac_f32_e32 v35, v12, v12
	v_fmac_f32_e32 v36, v14, v14
	v_fmac_f32_e32 v37, v8, v8
	v_fmac_f32_e32 v38, v10, v10
	s_waitcnt vmcnt(0)
	v_mul_f32_e32 v41, v1, v1
	v_mul_f32_e32 v42, v3, v3
	v_fmac_f32_e32 v39, v4, v4
	v_fmac_f32_e32 v40, v6, v6
	v_add_f32_e32 v35, v35, v36
	v_add_f32_e32 v36, v37, v38
	v_fmac_f32_e32 v41, v0, v0
	v_fmac_f32_e32 v42, v2, v2
	v_add_f32_e32 v37, v39, v40
	v_add_f32_e32 v35, v35, v36
	v_add_f32_e32 v35, v35, v37
	v_add_f32_e32 v36, v41, v42
	v_add_f32_e32 v35, v35, v36
	s_nop 1
	v_mov_b32_dpp v36, v35 quad_perm:[1,0,3,2] row_mask:0xf bank_mask:0xf
	s_waitcnt lgkmcnt(0)
	v_add_f32_e32 v35, v35, v36
	s_nop 1
	v_mov_b32_dpp v36, v35 quad_perm:[2,3,0,1] row_mask:0xf bank_mask:0xf
	s_waitcnt lgkmcnt(0)
	v_add_f32_e32 v35, v35, v36
	s_nop 1
	v_mov_b32_dpp v36, v35 row_half_mirror row_mask:0xf bank_mask:0xf
	s_waitcnt lgkmcnt(0)
	v_add_f32_e32 v35, v35, v36
	s_nop 1
	v_mov_b32_dpp v36, v35 row_mirror row_mask:0xf bank_mask:0xf
	s_waitcnt lgkmcnt(0)
	v_add_f32_e32 v35, v35, v36
	v_mov_b32_e32 v36, v35
	s_nop 1
	v_permlane16_swap_b32_e32 v36, v35
	s_waitcnt lgkmcnt(0)
	v_add_f32_e32 v35, v35, v36
	v_mov_b32_e32 v36, v35
	s_nop 1
	v_permlane32_swap_b32_e32 v36, v35
	s_and_saveexec_b64 s[30:31], s[4:5]
	s_cbranch_execz .LBB0_172
	s_add_u32 s38, s14, s36
	s_waitcnt lgkmcnt(0)
	v_add_f32_e32 v35, v35, v36
	s_addc_u32 s39, s15, s37
	global_store_dword v17, v35, s[38:39]
	s_branch .LBB0_172

.LBB0_180:
	global_load_dwordx4 v[98:101], v[86:87], off offset:-16
	global_load_dwordx4 v[106:109], v[86:87], off
	s_waitcnt vmcnt(1)
	v_and_b32_e32 v95, 0xffff0000, v98
	v_lshlrev_b32_e32 v93, 16, v98
	s_waitcnt lgkmcnt(0)
	v_lshlrev_b32_e32 v94, 16, v99
	v_and_b32_e32 v97, 0xffff0000, v99
	v_lshlrev_b32_e32 v96, 16, v100
	v_and_b32_e32 v99, 0xffff0000, v100
	s_waitcnt vmcnt(0)
	v_lshlrev_b32_e32 v100, 16, v106
	v_and_b32_e32 v103, 0xffff0000, v106
	v_lshlrev_b32_e32 v102, 16, v107
	v_and_b32_e32 v105, 0xffff0000, v107
	v_lshlrev_b32_e32 v104, 16, v108
	v_and_b32_e32 v107, 0xffff0000, v108
	v_lshlrev_b32_e32 v106, 16, v109
	v_and_b32_e32 v108, 0xffff0000, v109
	v_mul_f32_e32 v109, v1, v95
	v_mul_f32_e32 v110, v3, v97
	v_fmac_f32_e32 v109, v0, v93
	v_lshlrev_b32_e32 v98, 16, v101
	v_and_b32_e32 v101, 0xffff0000, v101
	v_mul_f32_e32 v111, v5, v99
	v_fmac_f32_e32 v110, v2, v94
	v_add_f32_e32 v109, 0, v109
	v_mul_f32_e32 v112, v7, v101
	v_fmac_f32_e32 v111, v4, v96
	v_add_f32_e32 v109, v110, v109
	v_mul_f32_e32 v113, v9, v103
	v_fmac_f32_e32 v112, v6, v98
	v_add_f32_e32 v109, v111, v109
	v_mul_f32_e32 v114, v11, v105
	v_fmac_f32_e32 v113, v8, v100
	v_add_f32_e32 v109, v112, v109
	v_mul_f32_e32 v115, v13, v107
	v_fmac_f32_e32 v114, v10, v102
	v_add_f32_e32 v109, v113, v109
	v_mul_f32_e32 v116, v15, v108
	v_fmac_f32_e32 v115, v12, v104
	v_add_f32_e32 v109, v114, v109
	v_add_f32_e32 v109, v115, v109
	v_fmac_f32_e32 v116, v14, v106
	v_add_f32_e32 v109, v116, v109
	v_mul_f32_e32 v118, v25, v95
	v_fmac_f32_e32 v118, v24, v93
	v_mul_f32_e32 v122, v27, v97
	v_add_f32_e32 v118, 0, v118
	v_fmac_f32_e32 v122, v26, v94
	v_add_f32_e32 v118, v122, v118
	v_mul_f32_e32 v122, v17, v99
	v_fmac_f32_e32 v122, v16, v96
	v_add_f32_e32 v118, v122, v118
	v_mul_f32_e32 v122, v19, v101
	v_fmac_f32_e32 v122, v18, v98
	v_add_f32_e32 v118, v122, v118
	v_mul_f32_e32 v122, v21, v103
	v_fmac_f32_e32 v122, v20, v100
	v_add_f32_e32 v118, v122, v118
	v_mul_f32_e32 v122, v23, v105
	v_fmac_f32_e32 v122, v22, v102
	v_add_f32_e32 v118, v122, v118
	v_mul_f32_e32 v122, v29, v107
	v_fmac_f32_e32 v122, v28, v104
	v_add_f32_e32 v118, v122, v118
	v_mul_f32_e32 v122, v31, v108
	v_fmac_f32_e32 v122, v30, v106
	v_add_f32_e32 v118, v122, v118
	v_mul_f32_e32 v119, v41, v95
	v_fmac_f32_e32 v119, v40, v93
	v_mul_f32_e32 v123, v43, v97
	v_add_f32_e32 v119, 0, v119
	v_fmac_f32_e32 v123, v42, v94
	v_add_f32_e32 v119, v123, v119
	v_mul_f32_e32 v123, v33, v99
	v_fmac_f32_e32 v123, v32, v96
	v_add_f32_e32 v119, v123, v119
	v_mul_f32_e32 v123, v35, v101
	v_fmac_f32_e32 v123, v34, v98
	v_add_f32_e32 v119, v123, v119
	v_mul_f32_e32 v123, v37, v103
	v_fmac_f32_e32 v123, v36, v100
	v_add_f32_e32 v119, v123, v119
	v_mul_f32_e32 v123, v39, v105
	v_fmac_f32_e32 v123, v38, v102
	v_add_f32_e32 v119, v123, v119
	v_mul_f32_e32 v123, v45, v107
	v_fmac_f32_e32 v123, v44, v104
	v_add_f32_e32 v119, v123, v119
	v_mul_f32_e32 v123, v47, v108
	v_fmac_f32_e32 v123, v46, v106
	v_add_f32_e32 v119, v123, v119
	v_mul_f32_e32 v120, v57, v95
	v_fmac_f32_e32 v120, v56, v93
	v_mul_f32_e32 v124, v59, v97
	v_add_f32_e32 v120, 0, v120
	v_fmac_f32_e32 v124, v58, v94
	v_add_f32_e32 v120, v124, v120
	v_mul_f32_e32 v124, v49, v99
	v_fmac_f32_e32 v124, v48, v96
	v_add_f32_e32 v120, v124, v120
	v_mul_f32_e32 v124, v51, v101
	v_fmac_f32_e32 v124, v50, v98
	v_add_f32_e32 v120, v124, v120
	v_mul_f32_e32 v124, v53, v103
	v_fmac_f32_e32 v124, v52, v100
	v_add_f32_e32 v120, v124, v120
	v_mul_f32_e32 v124, v55, v105
	v_fmac_f32_e32 v124, v54, v102
	v_add_f32_e32 v120, v124, v120
	v_mul_f32_e32 v124, v61, v107
	v_fmac_f32_e32 v124, v60, v104
	v_add_f32_e32 v120, v124, v120
	v_mul_f32_e32 v124, v63, v108
	v_fmac_f32_e32 v124, v62, v106
	v_add_f32_e32 v120, v124, v120
	v_mul_f32_e32 v95, v73, v95
	v_fmac_f32_e32 v95, v72, v93
	v_add_f32_e32 v93, 0, v95
	v_mul_f32_e32 v95, v75, v97
	v_fmac_f32_e32 v95, v74, v94
	v_mul_f32_e32 v94, v65, v99
	v_add_f32_e32 v93, v95, v93
	v_fmac_f32_e32 v94, v64, v96
	v_add_f32_e32 v93, v94, v93
	v_mul_f32_e32 v94, v67, v101
	v_fmac_f32_e32 v94, v66, v98
	v_add_f32_e32 v93, v94, v93
	v_mul_f32_e32 v94, v69, v103
	v_fmac_f32_e32 v94, v68, v100
	v_add_f32_e32 v93, v94, v93
	v_mul_f32_e32 v94, v71, v105
	v_fmac_f32_e32 v94, v70, v102
	v_add_f32_e32 v93, v94, v93
	v_mul_f32_e32 v94, v77, v107
	v_fmac_f32_e32 v94, v76, v104
	v_add_f32_e32 v93, v94, v93
	v_mul_f32_e32 v94, v79, v108
	v_fmac_f32_e32 v94, v78, v106
	v_add_f32_e32 v93, v94, v93
	s_nop 1
	v_mov_b32_dpp v110, v109 quad_perm:[1,0,3,2] row_mask:0xf bank_mask:0xf
	v_mov_b32_dpp v122, v118 quad_perm:[1,0,3,2] row_mask:0xf bank_mask:0xf
	v_mov_b32_dpp v123, v119 quad_perm:[1,0,3,2] row_mask:0xf bank_mask:0xf
	v_mov_b32_dpp v124, v120 quad_perm:[1,0,3,2] row_mask:0xf bank_mask:0xf
	v_mov_b32_dpp v94, v93 quad_perm:[1,0,3,2] row_mask:0xf bank_mask:0xf
	s_waitcnt lgkmcnt(0)
	v_add_f32_e32 v109, v109, v110
	v_add_f32_e32 v118, v118, v122
	v_add_f32_e32 v119, v119, v123
	v_add_f32_e32 v120, v120, v124
	v_add_f32_e32 v93, v93, v94
	s_nop 1
	v_mov_b32_dpp v110, v109 quad_perm:[2,3,0,1] row_mask:0xf bank_mask:0xf
	v_mov_b32_dpp v122, v118 quad_perm:[2,3,0,1] row_mask:0xf bank_mask:0xf
	v_mov_b32_dpp v123, v119 quad_perm:[2,3,0,1] row_mask:0xf bank_mask:0xf
	v_mov_b32_dpp v124, v120 quad_perm:[2,3,0,1] row_mask:0xf bank_mask:0xf
	v_mov_b32_dpp v94, v93 quad_perm:[2,3,0,1] row_mask:0xf bank_mask:0xf
	s_waitcnt lgkmcnt(0)
	v_add_f32_e32 v109, v109, v110
	v_add_f32_e32 v118, v118, v122
	v_add_f32_e32 v119, v119, v123
	v_add_f32_e32 v120, v120, v124
	v_add_f32_e32 v93, v93, v94
	s_nop 1
	v_mov_b32_dpp v110, v109 row_half_mirror row_mask:0xf bank_mask:0xf
	v_mov_b32_dpp v122, v118 row_half_mirror row_mask:0xf bank_mask:0xf
	v_mov_b32_dpp v123, v119 row_half_mirror row_mask:0xf bank_mask:0xf
	v_mov_b32_dpp v124, v120 row_half_mirror row_mask:0xf bank_mask:0xf
	v_mov_b32_dpp v94, v93 row_half_mirror row_mask:0xf bank_mask:0xf
	s_waitcnt lgkmcnt(0)
	v_add_f32_e32 v109, v109, v110
	v_add_f32_e32 v118, v118, v122
	v_add_f32_e32 v119, v119, v123
	v_add_f32_e32 v120, v120, v124
	v_add_f32_e32 v93, v93, v94
	s_nop 1
	v_mov_b32_dpp v110, v109 row_mirror row_mask:0xf bank_mask:0xf
	v_mov_b32_dpp v122, v118 row_mirror row_mask:0xf bank_mask:0xf
	v_mov_b32_dpp v123, v119 row_mirror row_mask:0xf bank_mask:0xf
	v_mov_b32_dpp v124, v120 row_mirror row_mask:0xf bank_mask:0xf
	v_mov_b32_dpp v94, v93 row_mirror row_mask:0xf bank_mask:0xf
	s_waitcnt lgkmcnt(0)
	v_add_f32_e32 v109, v109, v110
	v_add_f32_e32 v118, v118, v122
	v_add_f32_e32 v119, v119, v123
	v_add_f32_e32 v120, v120, v124
	v_add_f32_e32 v93, v93, v94
	v_mov_b32_e32 v110, v109
	v_mov_b32_e32 v122, v118
	v_mov_b32_e32 v123, v119
	v_mov_b32_e32 v124, v120
	v_mov_b32_e32 v94, v93
	s_nop 1
	v_permlane16_swap_b32_e32 v110, v109
	v_permlane16_swap_b32_e32 v122, v118
	v_permlane16_swap_b32_e32 v123, v119
	v_permlane16_swap_b32_e32 v124, v120
	v_permlane16_swap_b32_e32 v94, v93
	s_waitcnt lgkmcnt(0)
	v_add_f32_e32 v109, v109, v110
	v_add_f32_e32 v118, v118, v122
	v_add_f32_e32 v119, v119, v123
	v_add_f32_e32 v120, v120, v124
	v_add_f32_e32 v93, v93, v94
	v_mov_b32_e32 v110, v109
	v_mov_b32_e32 v122, v118
	v_mov_b32_e32 v123, v119
	v_mov_b32_e32 v124, v120
	v_mov_b32_e32 v94, v93
	s_nop 1
	v_permlane32_swap_b32_e32 v110, v109
	v_permlane32_swap_b32_e32 v122, v118
	v_permlane32_swap_b32_e32 v123, v119
	v_permlane32_swap_b32_e32 v124, v120
	v_permlane32_swap_b32_e32 v94, v93
	s_waitcnt lgkmcnt(0)
	v_add_f32_e32 v109, v109, v110
	v_add_f32_e32 v118, v118, v122
	v_add_f32_e32 v119, v119, v123
	v_add_f32_e32 v120, v120, v124
	v_add_f32_e32 v93, v93, v94
	s_and_saveexec_b64 s[26:27], vcc
	s_cbranch_execz .LBB0_179
	global_store_dword v81, v109, s[4:5]
	s_add_i32 s46, s38, s43
	s_ashr_i32 s47, s46, 31
	s_lshl_b64 s[46:47], s[46:47], 2
	s_add_u32 s46, s18, s46
	s_addc_u32 s47, s39, s47
	global_store_dword v81, v118, s[46:47]
	s_add_i32 s48, s40, s43
	s_ashr_i32 s49, s48, 31
	s_lshl_b64 s[48:49], s[48:49], 2
	s_add_u32 s48, s18, s48
	s_addc_u32 s49, s39, s49
	global_store_dword v81, v119, s[48:49]
	s_add_i32 s52, s41, s43
	s_ashr_i32 s53, s52, 31
	s_lshl_b64 s[52:53], s[52:53], 2
	s_add_u32 s52, s18, s52
	s_addc_u32 s53, s39, s53
	global_store_dword v81, v120, s[52:53]
	s_add_i32 s54, s42, s43
	s_ashr_i32 s55, s54, 31
	s_lshl_b64 s[54:55], s[54:55], 2
	s_add_u32 s54, s18, s54
	s_addc_u32 s55, s39, s55
	global_store_dword v81, v93, s[54:55]
	s_branch .LBB0_179
